# attention loop: LDS waits thinned to one per MFMA pair; ring slot indices kept pre-shifted, near/far thresholds in s100/s101 with the shift test folded into the near dispatch, duplicate counter remove
# baseline (speedup 1.0000x reference)
; #define SBAR() __builtin_amdgcn_sched_barrier(0)
; __device__ __forceinline__ int v_rd_base(int lane) { return ((lane & 3) << 3) | (((lane >> 2) & 3) << 6) | (((lane >> 4) & 1) << 5) | (((lane >> 5) & 1) << 11); }
; #define WAIT_BAR() asm volatile("s_waitcnt vmcnt(0) lgkmcnt(0)\n\ts_barrier" ::: "memory")
; #define NEAR(t) (KBASE(t) > qlo - 176)
; #define TABP(t) (tab + 4 * (qm - KBASE(t) + TAB_OFF - 59))
; #define ROT() do { s_prev = s_cur; s_cur = s_next; s_next = (s_next == NSLOT - 1) ? 0 : s_next + 1; } while (0)
; template <int VAR>
; __device__ __forceinline__ void dattn_block(const BlockRef& cur, const BlockRef& nxt, bool has_next, char* lds, Seam& S, const Outs& OU) {
;     ...
;     float l_reg = 0; f32x16 o[4] = {};
;     const lds_cptr vb3 = (lds_cptr)V_lds + v_rd_base(lane);
;     const int sw = (r32 >> 1) & 7; const char* Kl = K_lds + r32 * 128;
;     const bf16_t* Kh = cur.K; const bf16_t* Vh = cur.V;
;     ...
;     f32x16 pA0, pA1, pB0, pB1; bf16x8 pa0, pa1, pa2, pa3;
;     int s_prev = 0, s_cur = 0, s_next = 1;
;     ...
;     WAIT_BAR();
;     SBAR(); qkt(0, pA0, pA1, K_lds, r32, hi, S.qr);
;     startSM(pA0, pA1, NEAR(0), TABP(0), shift);
; #pragma unroll
;     for (int r = 0; r < 16; ++r) pA1[r] = __builtin_amdgcn_exp2f(pA1[r]);
;     WAIT_BAR();
;     ROT();
;     bf16x8 kp[4];
;     { const char* a0_ = Kl + s_cur * SHM_K + (((0 + hi) ^ sw) << 4); const char* a1_ = Kl + s_cur * SHM_K + (((2 + hi) ^ sw) << 4);
;       kp[0] = *reinterpret_cast<const bf16x8*>(a0_); kp[1] = *reinterpret_cast<const bf16x8*>(a0_ + 32 * 128); kp[2] = *reinterpret_cast<const bf16x8*>(a1_); kp[3] = *reinterpret_cast<const bf16x8*>(a1_ + 32 * 128); }
;     ...
;     const int TL1 = __builtin_amdgcn_readfirstlane((qlo + 31) / KVBLK + 1);
;     int t = 1;
;     for (; t + 1 < TL1; t += 2) { STEP(pB0, pB1, pA0, pA1, t); STEP(pA0, pA1, pB0, pB1, t + 1); }
.LBB0_354:
	s_waitcnt vmcnt(0) lgkmcnt(0)
	s_barrier
	s_add_i32 s0, s80, 0x10f
	ds_read_b128 v[174:177], v222 offset:57344
	ds_read_b128 v[170:173], v222 offset:61440
	ds_read_b128 v[166:169], v223 offset:57344
	ds_read_b128 v[162:165], v223 offset:61440
	s_lshr_b32 s84, s0, 6
	s_add_i32 s0, s62, 31
	s_ashr_i32 s1, s0, 31
	v_exp_f32_e32 v82, v36
	v_exp_f32_e32 v83, v37
	v_exp_f32_e32 v84, v38
	v_exp_f32_e32 v85, v39
	v_exp_f32_e32 v86, v40
	v_exp_f32_e32 v87, v41
	v_exp_f32_e32 v88, v42
	v_exp_f32_e32 v89, v43
	v_exp_f32_e32 v90, v44
	v_exp_f32_e32 v91, v45
	v_exp_f32_e32 v92, v46
	v_exp_f32_e32 v93, v47
	v_exp_f32_e32 v94, v48
	v_exp_f32_e32 v95, v49
	v_exp_f32_e32 v96, v50
	v_exp_f32_e32 v97, v51
	v_exp_f32_e32 v98, v54
	v_exp_f32_e32 v99, v55
	v_exp_f32_e32 v100, v52
	v_exp_f32_e32 v101, v53
	v_exp_f32_e32 v102, v58
	v_exp_f32_e32 v103, v59
	v_exp_f32_e32 v104, v56
	v_exp_f32_e32 v105, v57
	v_exp_f32_e32 v106, v64
	v_exp_f32_e32 v107, v65
	v_exp_f32_e32 v108, v62
	v_exp_f32_e32 v109, v63
	v_exp_f32_e32 v110, v60
	v_exp_f32_e32 v111, v61
	v_exp_f32_e32 v112, v3
	v_exp_f32_e32 v113, v66
	s_lshr_b32 s1, s1, 26
	s_add_i32 s0, s0, s1
	s_andn2_b64 vcc, exec, s[4:5]
	s_ashr_i32 s60, s0, 6
	s_cmpk_lt_i32 s62, 0x61
	s_cbranch_scc1 .LBB0_402
	s_lshl_b32 s87, s81, 10
	s_cmp_lg_u32 0, -1
	s_cselect_b32 s0, 0, 0
	s_add_i32 s87, s87, s0
	s_lshl_b32 s0, s20, 10
	s_add_i32 s0, s63, s0
	s_lshl_b32 s1, s81, 7
	v_lshl_add_u64 v[4:5], s[18:19], 0, v[198:199]
	v_mov_b32_e32 v227, 0
	s_add_i32 s0, s0, s1
	s_mov_b32 s67, 0
	s_add_i32 s88, s87, 0xc000
	v_cmp_neq_f32_e64 s[4:5], 0, v204
	v_add_u32_e32 v3, s0, v220
	v_lshl_add_u64 v[206:207], v[4:5], 0, s[40:41]
	s_movk_i32 s91, 0x2000
	s_movk_i32 s89, 0x80
	s_mov_b32 s20, 2
	v_mov_b64_e32 v[208:209], v[202:203]
	s_movk_i32 s86, 0x4000
	v_mov_b32_e32 v66, 0
	v_mov_b32_e32 v67, v227
	v_mov_b32_e32 v68, v227
	v_mov_b32_e32 v69, v227
	v_mov_b32_e32 v70, v227
	v_mov_b32_e32 v71, v227
	v_mov_b32_e32 v72, v227
	v_mov_b32_e32 v73, v227
	v_mov_b32_e32 v74, v227
	v_mov_b32_e32 v75, v227
	v_mov_b32_e32 v76, v227
	v_mov_b32_e32 v77, v227
	v_mov_b32_e32 v78, v227
	v_mov_b32_e32 v79, v227
	v_mov_b32_e32 v80, v227
	v_mov_b32_e32 v81, v227
	v_mov_b32_e32 v50, 0
	v_mov_b32_e32 v51, v227
	v_mov_b32_e32 v52, v227
	v_mov_b32_e32 v53, v227
	v_mov_b32_e32 v54, v227
	v_mov_b32_e32 v55, v227
	v_mov_b32_e32 v56, v227
	v_mov_b32_e32 v57, v227
	v_mov_b32_e32 v58, v227
	v_mov_b32_e32 v59, v227
	v_mov_b32_e32 v60, v227
	v_mov_b32_e32 v61, v227
	v_mov_b32_e32 v62, v227
	v_mov_b32_e32 v63, v227
	v_mov_b32_e32 v64, v227
	v_mov_b32_e32 v65, v227
	v_mov_b32_e32 v34, 0
	v_mov_b32_e32 v35, v227
	v_mov_b32_e32 v36, v227
	v_mov_b32_e32 v37, v227
	v_mov_b32_e32 v38, v227
	v_mov_b32_e32 v39, v227
	v_mov_b32_e32 v40, v227
	v_mov_b32_e32 v41, v227
	v_mov_b32_e32 v42, v227
	v_mov_b32_e32 v43, v227
	v_mov_b32_e32 v44, v227
	v_mov_b32_e32 v45, v227
	v_mov_b32_e32 v46, v227
	v_mov_b32_e32 v47, v227
	v_mov_b32_e32 v48, v227
	v_mov_b32_e32 v49, v227
	v_mov_b32_e32 v18, 0
	v_mov_b32_e32 v19, v227
	v_mov_b32_e32 v20, v227
	v_mov_b32_e32 v21, v227
	v_mov_b32_e32 v22, v227
	v_mov_b32_e32 v23, v227
	v_mov_b32_e32 v24, v227
	v_mov_b32_e32 v25, v227
	v_mov_b32_e32 v26, v227
	v_mov_b32_e32 v27, v227
	v_mov_b32_e32 v28, v227
	v_mov_b32_e32 v29, v227
	v_mov_b32_e32 v30, v227
	v_mov_b32_e32 v31, v227
	v_mov_b32_e32 v32, v227
	v_mov_b32_e32 v33, v227
	s_cmp_lg_u64 s[4:5], 0
	s_cselect_b32 s100, 0x80000000, s85
	s_add_i32 s101, s100, 64
	v_add_u32_e32 v237, v215, v216
	v_add_u32_e32 v238, v215, v217
	v_add_u32_e32 v239, v215, v218
	v_add_u32_e32 v240, v215, v219
.LBB0_356:
	s_add_i32 s62, s20, 1
	s_add_i32 m0, s67, s88
	s_lshl1_add_u32 s66, s86, s87
	v_lshl_add_u64 v[4:5], v[206:207], 0, s[44:45]
	global_load_lds_dwordx4 v[4:5], off
	s_waitcnt lgkmcnt(2)
	v_mfma_f32_32x32x16_bf16 v[130:145], v[174:177], v[146:149], 0
	v_add_f32_e32 v4, v82, v83
	v_add_f32_e32 v5, v84, v85
	v_add_f32_e32 v6, v4, v5
	v_cvt_pk_bf16_f32 v4, v82, v83
	v_cvt_pk_bf16_f32 v5, v84, v85
	v_add_f32_e32 v7, v86, v87
	v_add_f32_e32 v8, v88, v89
	v_mfma_f32_32x32x16_bf16 v[114:129], v[170:173], v[146:149], 0
	v_add_f32_e32 v7, v7, v8
	v_add_f32_e32 v8, v7, v6
	v_cvt_pk_bf16_f32 v6, v86, v87
	v_cvt_pk_bf16_f32 v7, v88, v89
	v_add_u32_e32 v9, s91, v239
	s_mov_b32 m0, s66
	ds_read_b128 v[14:17], v9 offset:49152
	ds_read_b128 v[86:89], v9 offset:53248
	global_load_lds_dwordx4 v[208:209], off
	s_waitcnt lgkmcnt(2)
	v_mfma_f32_32x32x16_bf16 v[130:145], v[166:169], v[150:153], v[130:145]
	v_add_f32_e32 v9, v90, v91
	v_add_f32_e32 v10, v92, v93
	v_add_f32_e32 v9, v9, v10
	v_add_f32_e32 v10, v9, v8
	v_cvt_pk_bf16_f32 v8, v90, v91
	v_cvt_pk_bf16_f32 v9, v92, v93
	v_add_f32_e32 v11, v94, v95
	v_add_f32_e32 v13, v96, v97
	v_mfma_f32_32x32x16_bf16 v[114:129], v[162:165], v[150:153], v[114:129]
	v_add_f32_e32 v11, v11, v13
	v_add_f32_e32 v13, v11, v10
	v_cvt_pk_bf16_f32 v10, v94, v95
	v_cvt_pk_bf16_f32 v11, v96, v97
	v_add_u32_e32 v12, s91, v240
	ds_read_b128 v[90:93], v12 offset:49152
	ds_read_b128 v[82:85], v12 offset:53248
	s_add_i32 m0, s66, 0x2000
	v_lshl_add_u64 v[94:95], v[208:209], 0, s[22:23]
	global_load_lds_dwordx4 v[94:95], off
	s_cmp_le_i32 s89, s101
	s_waitcnt lgkmcnt(2)
	v_mfma_f32_32x32x16_bf16 v[130:145], v[14:17], v[154:157], v[130:145]
	v_add_f32_e32 v12, v98, v99
	v_add_f32_e32 v94, v100, v101
	v_add_f32_e32 v12, v12, v94
	v_add_f32_e32 v94, v12, v13
	v_cvt_pk_bf16_f32 v12, v98, v99
	v_cvt_pk_bf16_f32 v13, v100, v101
	v_mfma_f32_32x32x16_bf16 v[114:129], v[86:89], v[154:157], v[114:129]
	v_add_f32_e32 v14, v102, v103
	v_add_f32_e32 v15, v104, v105
	v_add_f32_e32 v14, v14, v15
	v_add_f32_e32 v16, v14, v94
	v_cvt_pk_bf16_f32 v14, v102, v103
	v_cvt_pk_bf16_f32 v15, v104, v105
	s_waitcnt lgkmcnt(0)
	v_mfma_f32_32x32x16_bf16 v[130:145], v[90:93], v[158:161], v[130:145]
	v_add_f32_e32 v17, v106, v107
	v_add_f32_e32 v86, v108, v109
	v_add_f32_e32 v17, v17, v86
	v_add_f32_e32 v16, v17, v16
	v_cvt_pk_bf16_f32 v178, v106, v107
	v_cvt_pk_bf16_f32 v179, v108, v109
	v_add_f32_e32 v17, v110, v111
	v_add_f32_e32 v86, v112, v113
	v_add_f32_e32 v17, v17, v86
	v_add_f32_e32 v229, v17, v16
	v_cvt_pk_bf16_f32 v180, v110, v111
	v_cvt_pk_bf16_f32 v181, v112, v113
	v_lshl_add_u32 v16, s67, 1, v214
	v_mfma_f32_32x32x16_bf16 v[114:129], v[82:85], v[158:161], v[114:129]
	ds_read_b64_tr_b16 v[174:175], v16
	ds_read_b64_tr_b16 v[176:177], v16 offset:256
	ds_read_b64_tr_b16 v[170:171], v16 offset:4096
	ds_read_b64_tr_b16 v[172:173], v16 offset:4352
	ds_read_b64_tr_b16 v[166:167], v16 offset:8192
	ds_read_b64_tr_b16 v[168:169], v16 offset:8448
	ds_read_b64_tr_b16 v[162:163], v16 offset:12288
	ds_read_b64_tr_b16 v[164:165], v16 offset:12544
	s_cbranch_scc0 .Lp2s_disp1
; #define SBAR() __builtin_amdgcn_sched_barrier(0)
; template <int VAR> ...
;     ...
;     float ps = 0.f;
;     if constexpr (VAR & 4) { ka[0] = qr[0]; ka[1] = qr[1]; ka[2] = qr[2]; ka[3] = qr[3]; kb[0] = qr[0]; kb[1] = qr[1]; kb[2] = qr[2]; kb[3] = qr[3]; }
;     ka[0] = kp[0]; kb[0] = kp[1]; ka[1] = kp[2]; kb[1] = kp[3]; if (dk) glds16(gk, lk); SBAR();
;     { const f32x16 z = f32x16{};
;       QKM(x0, ka[0], qr[0], z);  SUM4(y0, 0); PKA(y0, 0);       SBAR();
;       QKM(x1, kb[0], qr[0], z);  SUM4(y0, 4); PKB(y0, 4, pa0);  KRD(2); if (dv) glds16(gv, lv); SBAR(); }
;     QKM(x0, ka[1], qr[1], x0); SUM4(y0, 8); PKA(y0, 8);       SBAR();
;     QKM(x1, kb[1], qr[1], x1); SUM4(y0, 12); PKB(y0, 12, pa1); KRD(3); if (dv) glds16(gv + 8192, lv + 8192); SBAR();
;     QKM(x0, ka[2], qr[2], x0); SUM4(y1, 0); PKA(y1, 0);       SBAR();
;     QKM(x1, kb[2], qr[2], x1); SUM4(y1, 4); PKB(y1, 4, pa2);  SBAR();
;     QKM(x0, ka[3], qr[3], x0); SUM4(y1, 8); PKA(y1, 8);       SBAR();
;     QKM(x1, kb[3], qr[3], x1); SUM4(y1, 12); PKB(y1, 12, pa3); VRD(0); VRD(1); SBAR();
;     VRD(2); VRD(3); SBAR();
;     if (near) {
;         float tA[4], uA[4], tB[4], uB[4];
;     ...
;         TLD(tA, uA, 0); SBAR(); TLD(tB, uB, 1); SBAR();
;         asm volatile("s_nop 15\n\ts_nop 7" : "+v"(x0), "+v"(x1));
;         TAD(tA, uA, 0); SBAR(); TLD(tA, uA, 2); SBAR(); TAD(tB, uB, 1); SBAR(); TLD(tB, uB, 3); SBAR(); TAD(tA, uA, 2); SBAR(); TAD(tB, uB, 3);
;     ...
;     } else if (__builtin_expect(shift != 0.f, 0)) {
;         asm volatile("s_nop 15\n\ts_nop 7" : "+v"(x0), "+v"(x1));
; #pragma unroll
;         for (int r = 0; r < 16; ++r) { asm volatile("v_sub_f32 %0, %0, %1" : "+v"(x0[r]) : "v"(shift)); asm volatile("v_sub_f32 %0, %0, %1" : "+v"(x1[r]) : "v"(shift)); }
;     }
;     SBAR();
;     ...
;     GAPB(0, pa0); GAPB(1, pa1); GAPB(2, pa2); GAPB(3, pa3); GAPB(4, pa0); GAPB(5, pa1); GAPB(6, pa2); GAPB(7, pa3);
;     GAPB(8, pa0); GAPB(9, pa1); GAPB(10, pa2); GAPB(11, pa3);
;     if (wv == 3) asm volatile("s_waitcnt vmcnt(3)" ::: "memory"); else if (wv == 2) asm volatile("s_waitcnt vmcnt(2)" ::: "memory"); else asm volatile("s_waitcnt vmcnt(0)" ::: "memory");
;     asm volatile("s_waitcnt lgkmcnt(0)\n\ts_barrier" ::: "memory");
;     if (pre) { const char* a0_ = Kn + (((0 + hi) ^ sw) << 4); const char* a1_ = Kn + (((2 + hi) ^ sw) << 4);
.LBB0_367:
	s_waitcnt lgkmcnt(4)
	v_mfma_f32_32x32x16_bf16 v[66:81], v[4:7], v[174:177], v[66:81]
	v_exp_f32_e32 v130, v130
	v_exp_f32_e32 v114, v114
	ds_read_b64_tr_b16 v[98:99], v16 offset:512
	ds_read_b64_tr_b16 v[100:101], v16 offset:768
	v_mfma_f32_32x32x16_bf16 v[66:81], v[8:11], v[170:173], v[66:81]
	v_exp_f32_e32 v131, v131
	v_exp_f32_e32 v115, v115
	ds_read_b64_tr_b16 v[102:103], v16 offset:4608
	ds_read_b64_tr_b16 v[104:105], v16 offset:4864
	s_waitcnt lgkmcnt(4)
	v_mfma_f32_32x32x16_bf16 v[66:81], v[12:15], v[166:169], v[66:81]
	v_exp_f32_e32 v132, v132
	v_exp_f32_e32 v116, v116
	ds_read_b64_tr_b16 v[106:107], v16 offset:8704
	ds_read_b64_tr_b16 v[108:109], v16 offset:8960
	v_mfma_f32_32x32x16_bf16 v[66:81], v[178:181], v[162:165], v[66:81]
	v_exp_f32_e32 v133, v133
	v_exp_f32_e32 v117, v117
	ds_read_b64_tr_b16 v[110:111], v16 offset:12800
	ds_read_b64_tr_b16 v[112:113], v16 offset:13056
	s_waitcnt lgkmcnt(4)
	v_mfma_f32_32x32x16_bf16 v[50:65], v[4:7], v[98:101], v[50:65]
	v_exp_f32_e32 v134, v134
	v_exp_f32_e32 v118, v118
	v_exp_f32_e32 v142, v142
	ds_read_b64_tr_b16 v[82:83], v16 offset:1024
	ds_read_b64_tr_b16 v[84:85], v16 offset:1280
	v_mfma_f32_32x32x16_bf16 v[50:65], v[8:11], v[102:105], v[50:65]
	v_exp_f32_e32 v135, v135
	v_exp_f32_e32 v119, v119
	v_exp_f32_e32 v126, v126
	ds_read_b64_tr_b16 v[86:87], v16 offset:5120
	ds_read_b64_tr_b16 v[88:89], v16 offset:5376
	s_waitcnt lgkmcnt(4)
	v_mfma_f32_32x32x16_bf16 v[50:65], v[12:15], v[106:109], v[50:65]
	v_exp_f32_e32 v136, v136
	v_exp_f32_e32 v120, v120
	v_exp_f32_e32 v143, v143
	ds_read_b64_tr_b16 v[90:91], v16 offset:9216
	ds_read_b64_tr_b16 v[92:93], v16 offset:9472
	v_mfma_f32_32x32x16_bf16 v[50:65], v[178:181], v[110:113], v[50:65]
	v_exp_f32_e32 v137, v137
	v_exp_f32_e32 v121, v121
	v_exp_f32_e32 v127, v127
	ds_read_b64_tr_b16 v[94:95], v16 offset:13312
	ds_read_b64_tr_b16 v[96:97], v16 offset:13568
	s_waitcnt lgkmcnt(4)
	v_mfma_f32_32x32x16_bf16 v[34:49], v[4:7], v[82:85], v[34:49]
	v_exp_f32_e32 v138, v138
	v_exp_f32_e32 v122, v122
	v_exp_f32_e32 v144, v144
	ds_read_b64_tr_b16 v[98:99], v16 offset:1536
	ds_read_b64_tr_b16 v[100:101], v16 offset:1792
	v_mfma_f32_32x32x16_bf16 v[34:49], v[8:11], v[86:89], v[34:49]
	v_exp_f32_e32 v139, v139
	v_exp_f32_e32 v123, v123
	v_exp_f32_e32 v128, v128
	ds_read_b64_tr_b16 v[102:103], v16 offset:5632
	ds_read_b64_tr_b16 v[104:105], v16 offset:5888
	s_waitcnt lgkmcnt(4)
	v_mfma_f32_32x32x16_bf16 v[34:49], v[12:15], v[90:93], v[34:49]
	v_exp_f32_e32 v140, v140
	v_exp_f32_e32 v124, v124
	v_exp_f32_e32 v145, v145
	ds_read_b64_tr_b16 v[106:107], v16 offset:9728
	ds_read_b64_tr_b16 v[108:109], v16 offset:9984
	v_mfma_f32_32x32x16_bf16 v[34:49], v[178:181], v[94:97], v[34:49]
	v_exp_f32_e32 v141, v141
	v_exp_f32_e32 v125, v125
	v_exp_f32_e32 v129, v129
	ds_read_b64_tr_b16 v[110:111], v16 offset:13824
	ds_read_b64_tr_b16 v[112:113], v16 offset:14080
	s_waitcnt vmcnt(3) lgkmcnt(0)
	s_barrier
	v_add_u32_e32 v16, s86, v237
	v_add_u32_e32 v17, s86, v238
	ds_read_b128 v[174:177], v16 offset:49152
	ds_read_b128 v[170:173], v16 offset:53248
	ds_read_b128 v[166:169], v17 offset:49152
	ds_read_b128 v[162:165], v17 offset:53248
	v_mfma_f32_32x32x16_bf16 v[18:33], v[4:7], v[98:101], v[18:33]
	v_mfma_f32_32x32x16_bf16 v[18:33], v[8:11], v[102:105], v[18:33]
	v_mfma_f32_32x32x16_bf16 v[18:33], v[12:15], v[106:109], v[18:33]
	v_mfma_f32_32x32x16_bf16 v[18:33], v[178:181], v[110:113], v[18:33]
	s_add_i32 s0, s86, 0x2000
	s_cmp_lg_u32 s86, 0x4000
	s_cselect_b32 s68, s0, 0
	s_add_i32 s20, s20, 2
	s_add_i32 m0, s91, s88
	s_lshl1_add_u32 s69, s68, s87
	global_load_lds_dwordx4 v[206:207], off
	v_lshl_add_u64 v[12:13], v[208:209], 0, s[26:27]
	s_waitcnt lgkmcnt(2)
	v_mfma_f32_32x32x16_bf16 v[82:97], v[174:177], v[146:149], 0
	v_add_f32_e32 v4, v130, v131
	v_add_f32_e32 v5, v132, v133
	v_add_f32_e32 v6, v4, v5
	v_cvt_pk_bf16_f32 v4, v130, v131
	v_cvt_pk_bf16_f32 v5, v132, v133
	v_add_f32_e32 v7, v134, v135
	v_add_f32_e32 v8, v136, v137
	v_mfma_f32_32x32x16_bf16 v[98:113], v[170:173], v[146:149], 0
	v_add_f32_e32 v7, v7, v8
	v_add_f32_e32 v8, v7, v6
	v_cvt_pk_bf16_f32 v6, v134, v135
	v_cvt_pk_bf16_f32 v7, v136, v137
	v_add_u32_e32 v9, s86, v239
	s_mov_b32 m0, s69
	ds_read_b128 v[14:17], v9 offset:49152
	ds_read_b128 v[130:133], v9 offset:53248
	global_load_lds_dwordx4 v[12:13], off
	s_waitcnt lgkmcnt(2)
	v_mfma_f32_32x32x16_bf16 v[82:97], v[166:169], v[150:153], v[82:97]
	v_add_f32_e32 v9, v138, v139
	v_add_f32_e32 v10, v140, v141
	v_add_f32_e32 v9, v9, v10
	v_add_f32_e32 v10, v9, v8
	v_cvt_pk_bf16_f32 v8, v138, v139
	v_cvt_pk_bf16_f32 v9, v140, v141
	v_add_f32_e32 v11, v142, v143
	v_add_f32_e32 v134, v144, v145
	v_mfma_f32_32x32x16_bf16 v[98:113], v[162:165], v[150:153], v[98:113]
	v_add_f32_e32 v11, v11, v134
	v_add_f32_e32 v178, v11, v10
	v_cvt_pk_bf16_f32 v10, v142, v143
	v_cvt_pk_bf16_f32 v11, v144, v145
	v_add_u32_e32 v134, s86, v240
	ds_read_b128 v[138:141], v134 offset:49152
	ds_read_b128 v[134:137], v134 offset:53248
	s_add_i32 m0, s69, 0x2000
	v_lshl_add_u64 v[12:13], v[12:13], 0, s[22:23]
	global_load_lds_dwordx4 v[12:13], off
	s_cmp_le_i32 s89, s100
	s_waitcnt lgkmcnt(2)
	v_mfma_f32_32x32x16_bf16 v[82:97], v[14:17], v[154:157], v[82:97]
	v_add_f32_e32 v12, v114, v115
	v_add_f32_e32 v13, v116, v117
	v_add_f32_e32 v12, v12, v13
	v_add_f32_e32 v142, v12, v178
	v_cvt_pk_bf16_f32 v12, v114, v115
	v_cvt_pk_bf16_f32 v13, v116, v117
	v_mfma_f32_32x32x16_bf16 v[98:113], v[130:133], v[154:157], v[98:113]
	v_add_f32_e32 v14, v118, v119
	v_add_f32_e32 v15, v120, v121
	v_add_f32_e32 v14, v14, v15
	v_add_f32_e32 v16, v14, v142
	v_cvt_pk_bf16_f32 v14, v118, v119
	v_cvt_pk_bf16_f32 v15, v120, v121
	s_waitcnt lgkmcnt(0)
	v_mfma_f32_32x32x16_bf16 v[82:97], v[138:141], v[158:161], v[82:97]
	v_add_f32_e32 v17, v122, v123
	v_add_f32_e32 v130, v124, v125
	v_add_f32_e32 v17, v17, v130
	v_add_f32_e32 v16, v17, v16
	v_cvt_pk_bf16_f32 v178, v122, v123
	v_cvt_pk_bf16_f32 v179, v124, v125
	v_add_f32_e32 v17, v126, v127
	v_add_f32_e32 v130, v128, v129
	v_add_f32_e32 v17, v17, v130
	v_add_f32_e32 v16, v17, v16
	v_cvt_pk_bf16_f32 v180, v126, v127
	v_cvt_pk_bf16_f32 v181, v128, v129
	v_lshl_add_u32 v17, s91, 1, v214
	v_mfma_f32_32x32x16_bf16 v[98:113], v[134:137], v[158:161], v[98:113]
	ds_read_b64_tr_b16 v[194:195], v17
	ds_read_b64_tr_b16 v[196:197], v17 offset:256
	ds_read_b64_tr_b16 v[190:191], v17 offset:4096
	ds_read_b64_tr_b16 v[192:193], v17 offset:4352
	ds_read_b64_tr_b16 v[186:187], v17 offset:8192
	ds_read_b64_tr_b16 v[188:189], v17 offset:8448
	ds_read_b64_tr_b16 v[182:183], v17 offset:12288
	ds_read_b64_tr_b16 v[184:185], v17 offset:12544
	s_cbranch_scc0 .Lp2s_disp2
; #define SBAR() __builtin_amdgcn_sched_barrier(0)
; template <int VAR> ...
;     ...
;     GAPB(0, pa0); GAPB(1, pa1); GAPB(2, pa2); GAPB(3, pa3); GAPB(4, pa0); GAPB(5, pa1); GAPB(6, pa2); GAPB(7, pa3);
;     GAPB(8, pa0); GAPB(9, pa1); GAPB(10, pa2); GAPB(11, pa3);
;     if (wv == 3) asm volatile("s_waitcnt vmcnt(3)" ::: "memory"); else if (wv == 2) asm volatile("s_waitcnt vmcnt(2)" ::: "memory"); else asm volatile("s_waitcnt vmcnt(0)" ::: "memory");
;     asm volatile("s_waitcnt lgkmcnt(0)\n\ts_barrier" ::: "memory");
;     if (pre) { const char* a0_ = Kn + (((0 + hi) ^ sw) << 4); const char* a1_ = Kn + (((2 + hi) ^ sw) << 4);
;         kp[0] = *reinterpret_cast<const bf16x8*>(a0_); kp[1] = *reinterpret_cast<const bf16x8*>(a0_ + 32 * 128); kp[2] = *reinterpret_cast<const bf16x8*>(a1_); kp[3] = *reinterpret_cast<const bf16x8*>(a1_ + 32 * 128); }
;     SBAR();
;     GAPB(12, pa0); GAPB(13, pa1); GAPB(14, pa2); GAPB(15, pa3);
; template <int VAR>
; __device__ __forceinline__ void dattn_block(const BlockRef& cur, const BlockRef& nxt, bool has_next, char* lds, Seam& S, const Outs& OU) {
;     ...
;     const int TL1 = __builtin_amdgcn_readfirstlane((qlo + 31) / KVBLK + 1);
;     int t = 1;
;     for (; t + 1 < TL1; t += 2) { STEP(pB0, pB1, pA0, pA1, t); STEP(pA0, pA1, pB0, pB1, t + 1); }
.LBB0_385:
	s_waitcnt lgkmcnt(4)
	v_mfma_f32_32x32x16_bf16 v[66:81], v[4:7], v[194:197], v[66:81]
	v_exp_f32_e32 v82, v82
	v_exp_f32_e32 v98, v98
	ds_read_b64_tr_b16 v[114:115], v17 offset:512
	ds_read_b64_tr_b16 v[116:117], v17 offset:768
	v_mfma_f32_32x32x16_bf16 v[66:81], v[8:11], v[190:193], v[66:81]
	v_exp_f32_e32 v83, v83
	v_exp_f32_e32 v99, v99
	ds_read_b64_tr_b16 v[118:119], v17 offset:4608
	ds_read_b64_tr_b16 v[120:121], v17 offset:4864
	s_waitcnt lgkmcnt(4)
	v_mfma_f32_32x32x16_bf16 v[66:81], v[12:15], v[186:189], v[66:81]
	v_exp_f32_e32 v84, v84
	v_exp_f32_e32 v100, v100
	ds_read_b64_tr_b16 v[122:123], v17 offset:8704
	ds_read_b64_tr_b16 v[124:125], v17 offset:8960
	v_mfma_f32_32x32x16_bf16 v[66:81], v[178:181], v[182:185], v[66:81]
	v_exp_f32_e32 v85, v85
	v_exp_f32_e32 v101, v101
	ds_read_b64_tr_b16 v[126:127], v17 offset:12800
	ds_read_b64_tr_b16 v[128:129], v17 offset:13056
	s_waitcnt lgkmcnt(4)
	v_mfma_f32_32x32x16_bf16 v[50:65], v[4:7], v[114:117], v[50:65]
	v_exp_f32_e32 v86, v86
	v_exp_f32_e32 v102, v102
	v_exp_f32_e32 v94, v94
	ds_read_b64_tr_b16 v[130:131], v17 offset:1024
	ds_read_b64_tr_b16 v[132:133], v17 offset:1280
	v_mfma_f32_32x32x16_bf16 v[50:65], v[8:11], v[118:121], v[50:65]
	v_exp_f32_e32 v87, v87
	v_exp_f32_e32 v103, v103
	v_exp_f32_e32 v110, v110
	ds_read_b64_tr_b16 v[134:135], v17 offset:5120
	ds_read_b64_tr_b16 v[136:137], v17 offset:5376
	s_waitcnt lgkmcnt(4)
	v_mfma_f32_32x32x16_bf16 v[50:65], v[12:15], v[122:125], v[50:65]
	v_exp_f32_e32 v88, v88
	v_exp_f32_e32 v104, v104
	v_exp_f32_e32 v95, v95
	ds_read_b64_tr_b16 v[138:139], v17 offset:9216
	ds_read_b64_tr_b16 v[140:141], v17 offset:9472
	v_mfma_f32_32x32x16_bf16 v[50:65], v[178:181], v[126:129], v[50:65]
	v_exp_f32_e32 v89, v89
	v_exp_f32_e32 v105, v105
	v_exp_f32_e32 v111, v111
	ds_read_b64_tr_b16 v[142:143], v17 offset:13312
	ds_read_b64_tr_b16 v[144:145], v17 offset:13568
	s_waitcnt lgkmcnt(4)
	v_mfma_f32_32x32x16_bf16 v[34:49], v[4:7], v[130:133], v[34:49]
	v_exp_f32_e32 v90, v90
	v_exp_f32_e32 v106, v106
	v_exp_f32_e32 v96, v96
	ds_read_b64_tr_b16 v[114:115], v17 offset:1536
	ds_read_b64_tr_b16 v[116:117], v17 offset:1792
	v_mfma_f32_32x32x16_bf16 v[34:49], v[8:11], v[134:137], v[34:49]
	v_exp_f32_e32 v91, v91
	v_exp_f32_e32 v107, v107
	v_exp_f32_e32 v112, v112
	ds_read_b64_tr_b16 v[118:119], v17 offset:5632
	ds_read_b64_tr_b16 v[120:121], v17 offset:5888
	s_waitcnt lgkmcnt(4)
	v_mfma_f32_32x32x16_bf16 v[34:49], v[12:15], v[138:141], v[34:49]
	v_exp_f32_e32 v92, v92
	v_exp_f32_e32 v108, v108
	v_exp_f32_e32 v97, v97
	ds_read_b64_tr_b16 v[122:123], v17 offset:9728
	ds_read_b64_tr_b16 v[124:125], v17 offset:9984
	v_mfma_f32_32x32x16_bf16 v[34:49], v[178:181], v[142:145], v[34:49]
	v_exp_f32_e32 v93, v93
	v_exp_f32_e32 v109, v109
	v_exp_f32_e32 v113, v113
	ds_read_b64_tr_b16 v[126:127], v17 offset:13824
	ds_read_b64_tr_b16 v[128:129], v17 offset:14080
	s_waitcnt vmcnt(3) lgkmcnt(0)
	s_barrier
	s_cmp_gt_i32 s62, s60
	s_cbranch_scc1 .LBB0_394
	v_add_u32_e32 v130, s68, v237
	v_add_u32_e32 v17, s68, v238
	ds_read_b128 v[174:177], v130 offset:49152
	ds_read_b128 v[170:173], v130 offset:53248
	ds_read_b128 v[166:169], v17 offset:49152
	ds_read_b128 v[162:165], v17 offset:53248
.LBB0_394:
	v_add_f32_e32 v17, v227, v229
	v_mfma_f32_32x32x16_bf16 v[18:33], v[4:7], v[114:117], v[18:33]
	v_mfma_f32_32x32x16_bf16 v[18:33], v[8:11], v[118:121], v[18:33]
	v_mfma_f32_32x32x16_bf16 v[18:33], v[12:15], v[122:125], v[18:33]
	v_mfma_f32_32x32x16_bf16 v[18:33], v[178:181], v[126:129], v[18:33]
	s_add_i32 s0, s68, 0x2000
	s_cmp_lg_u32 s68, 0x4000
	s_cselect_b32 s66, s0, 0
	s_addk_i32 s89, 0x80
	v_add_f32_e32 v227, v17, v16
	v_add_u32_e32 v3, 0xfffffe00, v3
	v_lshl_add_u64 v[208:209], v[208:209], 0, s[40:41]
	s_cmp_lt_i32 s62, s60
	v_lshl_add_u64 v[206:207], v[206:207], 0, s[26:27]
	s_cbranch_scc0 .LBB0_403
	s_mov_b32 s67, s86
	s_mov_b32 s91, s68
	s_mov_b32 s86, s66
	s_branch .LBB0_356

; #define SBAR() __builtin_amdgcn_sched_barrier(0)
; #define TLD(T, U, g) do { _Pragma("unroll") for (int j = 0; j < 4; ++j) { const int r_ = 4 * (g) + j, c_ = (r_ & 3) + 8 * (r_ >> 2); T[j] = *(const float*)(tabp + 4 * (59 - c_)); U[j] = *(const float*)(tabp + 4 * (59 - c_ - 32)); } } while (0)
; #define TAD(T, U, g) do { _Pragma("unroll") for (int j = 0; j < 4; ++j) { const int r_ = 4 * (g) + j; asm volatile("v_add_f32 %0, %0, %1" : "+v"(x0[r_]) : "v"(T[j])); asm volatile("v_add_f32 %0, %0, %1" : "+v"(x1[r_]) : "v"(U[j])); } } while (0)
; template <int VAR> ...
;     ...
;     if (near) {
;         float tA[4], uA[4], tB[4], uB[4];
;     ...
;         TLD(tA, uA, 0); SBAR(); TLD(tB, uB, 1); SBAR();
;         asm volatile("s_nop 15\n\ts_nop 7" : "+v"(x0), "+v"(x1));
;         TAD(tA, uA, 0); SBAR(); TLD(tA, uA, 2); SBAR(); TAD(tB, uB, 1); SBAR(); TLD(tB, uB, 3); SBAR(); TAD(tA, uA, 2); SBAR(); TAD(tB, uB, 3);
;     ...
;     } else if (__builtin_expect(shift != 0.f, 0)) {
.Lp2s_disp1:
	s_sub_i32 s2, s89, 64
	s_cmp_le_i32 s2, s85
	s_cbranch_scc1 .Lp2t_shift1

; #define SBAR() __builtin_amdgcn_sched_barrier(0)
; #define TLD(T, U, g) do { _Pragma("unroll") for (int j = 0; j < 4; ++j) { const int r_ = 4 * (g) + j, c_ = (r_ & 3) + 8 * (r_ >> 2); T[j] = *(const float*)(tabp + 4 * (59 - c_)); U[j] = *(const float*)(tabp + 4 * (59 - c_ - 32)); } } while (0)
; #define TAD(T, U, g) do { _Pragma("unroll") for (int j = 0; j < 4; ++j) { const int r_ = 4 * (g) + j; asm volatile("v_add_f32 %0, %0, %1" : "+v"(x0[r_]) : "v"(T[j])); asm volatile("v_add_f32 %0, %0, %1" : "+v"(x1[r_]) : "v"(U[j])); } } while (0)
; template <int VAR> ...
;     ...
;     if (near) {
;         float tA[4], uA[4], tB[4], uB[4];
;     ...
;         TLD(tA, uA, 0); SBAR(); TLD(tB, uB, 1); SBAR();
;         asm volatile("s_nop 15\n\ts_nop 7" : "+v"(x0), "+v"(x1));
;         TAD(tA, uA, 0); SBAR(); TLD(tA, uA, 2); SBAR(); TAD(tB, uB, 1); SBAR(); TLD(tB, uB, 3); SBAR(); TAD(tA, uA, 2); SBAR(); TAD(tB, uB, 3);
;     ...
;     } else if (__builtin_expect(shift != 0.f, 0)) {
.Lp2s_disp2:
	s_cmp_le_i32 s89, s85
	s_cbranch_scc1 .Lp2t_shift2

; #define SBAR() __builtin_amdgcn_sched_barrier(0)
; __device__ __forceinline__ int v_rd_base(int lane) { return ((lane & 3) << 3) | (((lane >> 2) & 3) << 6) | (((lane >> 4) & 1) << 5) | (((lane >> 5) & 1) << 11); }
; #define STAGE_ISSUE(t) do { if ((t) + 2 < NT) DMA_K(Kh, (t) + 2, s_prev); if ((t) + 1 < NT) DMA_V(Vh, (t) + 1, s_next); } while (0)
; #define STAGE_CLOSE(t) do { if ((t) + 2 < NT) { VMW_N(3); } else if ((t) + 1 < NT) { VMW_N(2); } else { VMW_N(0); } asm volatile("s_waitcnt lgkmcnt(0)\n\ts_barrier" ::: "memory"); ROT(); } while (0)
; template <int VAR>
; __device__ __forceinline__ void dattn_block(const BlockRef& cur, const BlockRef& nxt, bool has_next, char* lds, Seam& S, const Outs& OU) {
;     ...
;     if (t < TL1) {
;         STEP(pB0, pB1, pA0, pA1, t);
;         pA0 = pB0; pA1 = pB1;
;     }
;     ...
;     if (TL1 < NT) STAGE_ISSUE(TL1);
;     int tid_t = threadIdx.x; asm volatile("" : "+v"(tid_t));
;     const int lane_t = tid_t & 63, r32_t = lane_t & 31, hi_t = lane_t >> 5;
;     const int vb0_t = (int)(uintptr_t)V_lds + v_rd_base(lane_t) + s_prev * SHM_V;
;     finishSM<false>(pA0, pA1, l_reg, pa0, pa1, pa2, pa3); SBAR();
;     pv_tile(o, vb0_t, pa0, pa1, pa2, pa3);
;     for (int ti = TL1; ti < NT; ++ti) { if (ti > TL1) STAGE_ISSUE(ti); STAGE_CLOSE(ti); }
.LBB0_403:
	s_waitcnt lgkmcnt(0)
	s_lshr_b32 s86, s86, 13
	s_lshr_b32 s68, s68, 13
	s_lshr_b32 s66, s66, 13
	s_lshl_b64 s[4:5], s[20:21], 14
	s_cmp_gt_i32 s62, s60
	s_cbranch_scc1 .LBB0_423

; __global__ void __launch_bounds__(NWAVES * 64, 2) mega_fwd(Args args) {
;     extern __shared__ __attribute__((aligned(16))) unsigned char lds[];
	.amdhsa_kernel _Z8mega_fwd4Args
		.amdhsa_group_segment_fixed_size 0
		.amdhsa_private_segment_fixed_size 0
		.amdhsa_kernarg_size 408
		.amdhsa_user_sgpr_count 2
		.amdhsa_user_sgpr_dispatch_ptr 0
		.amdhsa_user_sgpr_queue_ptr 0
		.amdhsa_user_sgpr_kernarg_segment_ptr 1
		.amdhsa_user_sgpr_dispatch_id 0
		.amdhsa_user_sgpr_kernarg_preload_length 0
		.amdhsa_user_sgpr_kernarg_preload_offset 0
		.amdhsa_user_sgpr_private_segment_size 0
		.amdhsa_uses_dynamic_stack 0
		.amdhsa_enable_private_segment 0
		.amdhsa_system_sgpr_workgroup_id_x 1
		.amdhsa_system_sgpr_workgroup_id_y 0
		.amdhsa_system_sgpr_workgroup_id_z 0
		.amdhsa_system_sgpr_workgroup_info 0
		.amdhsa_system_vgpr_workitem_id 0
		.amdhsa_next_free_vgpr 241
		.amdhsa_next_free_sgpr 102
		.amdhsa_accum_offset 244
		.amdhsa_reserve_vcc 1
		.amdhsa_float_round_mode_32 0
		.amdhsa_float_round_mode_16_64 0
		.amdhsa_float_denorm_mode_32 3
		.amdhsa_float_denorm_mode_16_64 3
		.amdhsa_dx10_clamp 1
		.amdhsa_ieee_mode 1
		.amdhsa_fp16_overflow 0
		.amdhsa_tg_split 0
		.amdhsa_exception_fp_ieee_invalid_op 0
		.amdhsa_exception_fp_denorm_src 0
		.amdhsa_exception_fp_ieee_div_zero 0
		.amdhsa_exception_fp_ieee_overflow 0
		.amdhsa_exception_fp_ieee_underflow 0
		.amdhsa_exception_fp_ieee_inexact 0
		.amdhsa_exception_int_div_zero 0
	.end_amdhsa_kernel

; __global__ void __launch_bounds__(NWAVES * 64, 2) mega_fwd(Args args) {
;     extern __shared__ __attribute__((aligned(16))) unsigned char lds[];
amdhsa.kernels:
  - .agpr_count:     0
    .args:
      - .offset:         0
        .size:           152
        .value_kind:     by_value
      - .offset:         152
        .size:           4
        .value_kind:     hidden_block_count_x
      - .offset:         156
        .size:           4
        .value_kind:     hidden_block_count_y
      - .offset:         160
        .size:           4
        .value_kind:     hidden_block_count_z
      - .offset:         164
        .size:           2
        .value_kind:     hidden_group_size_x
      - .offset:         166
        .size:           2
        .value_kind:     hidden_group_size_y
      - .offset:         168
        .size:           2
        .value_kind:     hidden_group_size_z
      - .offset:         170
        .size:           2
        .value_kind:     hidden_remainder_x
      - .offset:         172
        .size:           2
        .value_kind:     hidden_remainder_y
      - .offset:         174
        .size:           2
        .value_kind:     hidden_remainder_z
      - .offset:         192
        .size:           8
        .value_kind:     hidden_global_offset_x
      - .offset:         200
        .size:           8
        .value_kind:     hidden_global_offset_y
      - .offset:         208
        .size:           8
        .value_kind:     hidden_global_offset_z
      - .offset:         216
        .size:           2
        .value_kind:     hidden_grid_dims
      - .offset:         272
        .size:           4
        .value_kind:     hidden_dynamic_lds_size
    .group_segment_fixed_size: 0
    .kernarg_segment_align: 8
    .kernarg_segment_size: 408
    .language:       OpenCL C
    .language_version:
      - 2
      - 0
    .max_flat_workgroup_size: 512
    .name:           _Z8mega_fwd4Args
    .private_segment_fixed_size: 0
    .sgpr_count:     108
    .sgpr_spill_count: 23
    .symbol:         _Z8mega_fwd4Args.kd
    .uniform_work_group_size: 1
    .uses_dynamic_stack: false
    .vgpr_count:     241
    .vgpr_spill_count: 0
    .wavefront_size: 64
